# inproj: the mixed-tile epilogue paths (Pt 8-byte stores, transposed VtAD 2-byte stores) also marked nt, like the row-store paths
# baseline (speedup 1.0000x reference)
; DI u16 f2bf(float x) { return (u16)(pack2(x, 0.f) & 0xffffu); }
; DI int crow(int i, int h) { return (i & 3) + 8 * (i >> 2) + 4 * h; }
; DI void phase_inproj(const Params& p, int l, char* smem, int tid) {
;     ...
; #pragma unroll
;     for (int mb = 0; mb < 2; mb++)
; #pragma unroll
;       for (int nb = 0; nb < 2; nb++) {
;         const int rowb = m0 + wm * 64 + mb * 32, colb = n0 + wn * 64 + nb * 32, col = colb + r;
;         if (colb < 1792) {
;           const float qs = (colb < 256) ? 0.125f * LOG2E : 1.f;
; #pragma unroll
;           for (int i = 0; i < 16; i++) p.Pk[(size_t)(rowb + crow(i, h)) * PKW + col] = f2bf(acc[mb][nb][i] * qs);
;         } else if (colb < 2592) {
; #pragma unroll
;           for (int i = 0; i < 16; i++) p.Pt[(size_t)(rowb + crow(i, h)) * PTW + col - 1792] = f2bf(acc[mb][nb][i]);
;         }
;       }
; #pragma unroll
;     for (int nb = 0; nb < 2; nb++) {
;       const int colb = n0 + wn * 64 + nb * 32;
;       if (colb >= 2592 && colb < 2976) {
;         const int rw = m0 + wm * 64;
;         float v[2][16];
; #pragma unroll
;         for (int mb = 0; mb < 2; mb++)
; #pragma unroll
;           for (int i = 0; i < 16; i++) v[mb][i] = acc[mb][nb][i];
;         vt_store32(v, (u16*)smem + w * (32 * 72), p.VtAD + ((size_t)(rw / SEQA) * 384 + colb - 2592) * SEQA + rw % SEQA, lane);
;       }
.Lip_e0_pk_noscale:
	v_cvt_pk_bf16_f32 v66, v2, v3
	v_cvt_pk_bf16_f32 v67, v4, v5
	global_store_dwordx2 v110, v[66:67], s[6:7] offset:0 nt
	v_cvt_pk_bf16_f32 v68, v6, v7
	v_cvt_pk_bf16_f32 v69, v8, v9
	global_store_dwordx2 v110, v[68:69], s[6:7] offset:16 nt
	v_cvt_pk_bf16_f32 v70, v10, v11
	v_cvt_pk_bf16_f32 v71, v12, v13
	global_store_dwordx2 v110, v[70:71], s[6:7] offset:32 nt
	v_cvt_pk_bf16_f32 v72, v14, v15
	v_cvt_pk_bf16_f32 v73, v16, v17
	global_store_dwordx2 v110, v[72:73], s[6:7] offset:48 nt
	v_cvt_pk_bf16_f32 v66, v34, v35
	v_cvt_pk_bf16_f32 v67, v36, v37
	global_store_dwordx2 v110, v[66:67], s[2:3] offset:0 nt
	v_cvt_pk_bf16_f32 v68, v38, v39
	v_cvt_pk_bf16_f32 v69, v40, v41
	global_store_dwordx2 v110, v[68:69], s[2:3] offset:16 nt
	v_cvt_pk_bf16_f32 v70, v42, v43
	v_cvt_pk_bf16_f32 v71, v44, v45
	global_store_dwordx2 v110, v[70:71], s[2:3] offset:32 nt
	v_cvt_pk_bf16_f32 v72, v46, v47
	v_cvt_pk_bf16_f32 v73, v48, v49
	global_store_dwordx2 v110, v[72:73], s[2:3] offset:48 nt
	s_branch .Lip_e0_end
.Lip_e0_pt:
	s_mul_i32 s2, s0, 0x32000
	s_sub_u32 s3, s16, 0x700
	s_lshl_b32 s3, s3, 1
	s_add_u32 s2, s2, s3
	s_add_u32 s2, s2, 0xbb00000
	s_add_u32 s6, s96, s2
	s_addc_u32 s7, s97, 0
	s_add_u32 s2, s6, 0xc800
	s_addc_u32 s3, s7, 0
	v_cvt_pk_bf16_f32 v66, v2, v3
	v_cvt_pk_bf16_f32 v67, v4, v5
	global_store_dwordx2 v111, v[66:67], s[6:7] offset:0 nt
	v_cvt_pk_bf16_f32 v68, v6, v7
	v_cvt_pk_bf16_f32 v69, v8, v9
	global_store_dwordx2 v111, v[68:69], s[6:7] offset:16 nt
	v_cvt_pk_bf16_f32 v70, v10, v11
	v_cvt_pk_bf16_f32 v71, v12, v13
	global_store_dwordx2 v111, v[70:71], s[6:7] offset:32 nt
	v_cvt_pk_bf16_f32 v72, v14, v15
	v_cvt_pk_bf16_f32 v73, v16, v17
	global_store_dwordx2 v111, v[72:73], s[6:7] offset:48 nt
	v_cvt_pk_bf16_f32 v66, v34, v35
	v_cvt_pk_bf16_f32 v67, v36, v37
	global_store_dwordx2 v111, v[66:67], s[2:3] offset:0 nt
	v_cvt_pk_bf16_f32 v68, v38, v39
	v_cvt_pk_bf16_f32 v69, v40, v41
	global_store_dwordx2 v111, v[68:69], s[2:3] offset:16 nt
	v_cvt_pk_bf16_f32 v70, v42, v43
	v_cvt_pk_bf16_f32 v71, v44, v45
	global_store_dwordx2 v111, v[70:71], s[2:3] offset:32 nt
	v_cvt_pk_bf16_f32 v72, v46, v47
	v_cvt_pk_bf16_f32 v73, v48, v49
	global_store_dwordx2 v111, v[72:73], s[2:3] offset:48 nt
	s_branch .Lip_e0_end
.Lip_e0_vt:
	s_mul_hi_u32 s2, s0, 0x78787879
	s_lshr_b32 s2, s2, 4
	s_mul_i32 s3, s2, 34
	s_sub_u32 s3, s0, s3
	s_lshl_b32 s3, s3, 8
	s_mul_i32 s2, s2, 0x330000
	s_add_u32 s2, s2, s3
	s_sub_u32 s3, s16, 0xa20
	s_mul_i32 s3, s3, 0x2200
	s_add_u32 s2, s2, s3
	s_add_u32 s2, s2, 0xf020000
	s_add_u32 s6, s96, s2
	s_addc_u32 s7, s97, 0
	v_add_u32_e32 v74, 0x0, v112
	v_cvt_pk_bf16_f32 v66, v2, v2
	global_store_short v74, v66, s[6:7] nt
	v_add_u32_e32 v75, 0x2200, v112
	v_cvt_pk_bf16_f32 v68, v3, v3
	global_store_short v75, v68, s[6:7] nt
	v_add_u32_e32 v76, 0x4400, v112
	v_cvt_pk_bf16_f32 v70, v4, v4
	global_store_short v76, v70, s[6:7] nt
	v_add_u32_e32 v77, 0x6600, v112
	v_cvt_pk_bf16_f32 v72, v5, v5
	global_store_short v77, v72, s[6:7] nt
	v_add_u32_e32 v74, 0x11000, v112
	v_cvt_pk_bf16_f32 v66, v6, v6
	global_store_short v74, v66, s[6:7] nt
	v_add_u32_e32 v75, 0x13200, v112
	v_cvt_pk_bf16_f32 v68, v7, v7
	global_store_short v75, v68, s[6:7] nt
	v_add_u32_e32 v76, 0x15400, v112
	v_cvt_pk_bf16_f32 v70, v8, v8
	global_store_short v76, v70, s[6:7] nt
	v_add_u32_e32 v77, 0x17600, v112
	v_cvt_pk_bf16_f32 v72, v9, v9
	global_store_short v77, v72, s[6:7] nt
	v_add_u32_e32 v74, 0x22000, v112
	v_cvt_pk_bf16_f32 v66, v10, v10
	global_store_short v74, v66, s[6:7] nt
	v_add_u32_e32 v75, 0x24200, v112
	v_cvt_pk_bf16_f32 v68, v11, v11
	global_store_short v75, v68, s[6:7] nt
	v_add_u32_e32 v76, 0x26400, v112
	v_cvt_pk_bf16_f32 v70, v12, v12
	global_store_short v76, v70, s[6:7] nt
	v_add_u32_e32 v77, 0x28600, v112
	v_cvt_pk_bf16_f32 v72, v13, v13
	global_store_short v77, v72, s[6:7] nt
	v_add_u32_e32 v74, 0x33000, v112
	v_cvt_pk_bf16_f32 v66, v14, v14
	global_store_short v74, v66, s[6:7] nt
	v_add_u32_e32 v75, 0x35200, v112
	v_cvt_pk_bf16_f32 v68, v15, v15
	global_store_short v75, v68, s[6:7] nt
	v_add_u32_e32 v76, 0x37400, v112
	v_cvt_pk_bf16_f32 v70, v16, v16
	global_store_short v76, v70, s[6:7] nt
	v_add_u32_e32 v77, 0x39600, v112
	v_cvt_pk_bf16_f32 v72, v17, v17
	global_store_short v77, v72, s[6:7] nt
	v_add_u32_e32 v74, 0x40, v112
	v_cvt_pk_bf16_f32 v66, v34, v34
	global_store_short v74, v66, s[6:7] nt
	v_add_u32_e32 v75, 0x2240, v112
	v_cvt_pk_bf16_f32 v68, v35, v35
	global_store_short v75, v68, s[6:7] nt
	v_add_u32_e32 v76, 0x4440, v112
	v_cvt_pk_bf16_f32 v70, v36, v36
	global_store_short v76, v70, s[6:7] nt
	v_add_u32_e32 v77, 0x6640, v112
	v_cvt_pk_bf16_f32 v72, v37, v37
	global_store_short v77, v72, s[6:7] nt
	v_add_u32_e32 v74, 0x11040, v112
	v_cvt_pk_bf16_f32 v66, v38, v38
	global_store_short v74, v66, s[6:7] nt
	v_add_u32_e32 v75, 0x13240, v112
	v_cvt_pk_bf16_f32 v68, v39, v39
	global_store_short v75, v68, s[6:7] nt
	v_add_u32_e32 v76, 0x15440, v112
	v_cvt_pk_bf16_f32 v70, v40, v40
	global_store_short v76, v70, s[6:7] nt
	v_add_u32_e32 v77, 0x17640, v112
	v_cvt_pk_bf16_f32 v72, v41, v41
	global_store_short v77, v72, s[6:7] nt
	v_add_u32_e32 v74, 0x22040, v112
	v_cvt_pk_bf16_f32 v66, v42, v42
	global_store_short v74, v66, s[6:7] nt
	v_add_u32_e32 v75, 0x24240, v112
	v_cvt_pk_bf16_f32 v68, v43, v43
	global_store_short v75, v68, s[6:7] nt
	v_add_u32_e32 v76, 0x26440, v112
	v_cvt_pk_bf16_f32 v70, v44, v44
	global_store_short v76, v70, s[6:7] nt
	v_add_u32_e32 v77, 0x28640, v112
	v_cvt_pk_bf16_f32 v72, v45, v45
	global_store_short v77, v72, s[6:7] nt
	v_add_u32_e32 v74, 0x33040, v112
	v_cvt_pk_bf16_f32 v66, v46, v46
	global_store_short v74, v66, s[6:7] nt
	v_add_u32_e32 v75, 0x35240, v112
	v_cvt_pk_bf16_f32 v68, v47, v47
	global_store_short v75, v68, s[6:7] nt
	v_add_u32_e32 v76, 0x37440, v112
	v_cvt_pk_bf16_f32 v70, v48, v48
	global_store_short v76, v70, s[6:7] nt
	v_add_u32_e32 v77, 0x39640, v112
	v_cvt_pk_bf16_f32 v72, v49, v49
	global_store_short v77, v72, s[6:7] nt

; DI u16 f2bf(float x) { return (u16)(pack2(x, 0.f) & 0xffffu); }
; DI int crow(int i, int h) { return (i & 3) + 8 * (i >> 2) + 4 * h; }
; DI void phase_inproj(const Params& p, int l, char* smem, int tid) {
;     ...
; #pragma unroll
;     for (int mb = 0; mb < 2; mb++)
; #pragma unroll
;       for (int nb = 0; nb < 2; nb++) {
;         const int rowb = m0 + wm * 64 + mb * 32, colb = n0 + wn * 64 + nb * 32, col = colb + r;
;         if (colb < 1792) {
;           const float qs = (colb < 256) ? 0.125f * LOG2E : 1.f;
; #pragma unroll
;           for (int i = 0; i < 16; i++) p.Pk[(size_t)(rowb + crow(i, h)) * PKW + col] = f2bf(acc[mb][nb][i] * qs);
;         } else if (colb < 2592) {
; #pragma unroll
;           for (int i = 0; i < 16; i++) p.Pt[(size_t)(rowb + crow(i, h)) * PTW + col - 1792] = f2bf(acc[mb][nb][i]);
;         }
;       }
; #pragma unroll
;     for (int nb = 0; nb < 2; nb++) {
;       const int colb = n0 + wn * 64 + nb * 32;
;       if (colb >= 2592 && colb < 2976) {
;         const int rw = m0 + wm * 64;
;         float v[2][16];
; #pragma unroll
;         for (int mb = 0; mb < 2; mb++)
; #pragma unroll
;           for (int i = 0; i < 16; i++) v[mb][i] = acc[mb][nb][i];
;         vt_store32(v, (u16*)smem + w * (32 * 72), p.VtAD + ((size_t)(rw / SEQA) * 384 + colb - 2592) * SEQA + rw % SEQA, lane);
;       }
.Lip_e1_pk_noscale:
	v_cvt_pk_bf16_f32 v66, v18, v19
	v_cvt_pk_bf16_f32 v67, v20, v21
	global_store_dwordx2 v110, v[66:67], s[6:7] offset:0 nt
	v_cvt_pk_bf16_f32 v68, v22, v23
	v_cvt_pk_bf16_f32 v69, v24, v25
	global_store_dwordx2 v110, v[68:69], s[6:7] offset:16 nt
	v_cvt_pk_bf16_f32 v70, v26, v27
	v_cvt_pk_bf16_f32 v71, v28, v29
	global_store_dwordx2 v110, v[70:71], s[6:7] offset:32 nt
	v_cvt_pk_bf16_f32 v72, v30, v31
	v_cvt_pk_bf16_f32 v73, v32, v33
	global_store_dwordx2 v110, v[72:73], s[6:7] offset:48 nt
	v_cvt_pk_bf16_f32 v66, v50, v51
	v_cvt_pk_bf16_f32 v67, v52, v53
	global_store_dwordx2 v110, v[66:67], s[2:3] offset:0 nt
	v_cvt_pk_bf16_f32 v68, v54, v55
	v_cvt_pk_bf16_f32 v69, v56, v57
	global_store_dwordx2 v110, v[68:69], s[2:3] offset:16 nt
	v_cvt_pk_bf16_f32 v70, v58, v59
	v_cvt_pk_bf16_f32 v71, v60, v61
	global_store_dwordx2 v110, v[70:71], s[2:3] offset:32 nt
	v_cvt_pk_bf16_f32 v72, v62, v63
	v_cvt_pk_bf16_f32 v73, v64, v65
	global_store_dwordx2 v110, v[72:73], s[2:3] offset:48 nt
	s_branch .Lip_e1_end
.Lip_e1_pt:
	s_mul_i32 s2, s0, 0x32000
	s_sub_u32 s3, s16, 0x700
	s_lshl_b32 s3, s3, 1
	s_add_u32 s2, s2, s3
	s_add_u32 s2, s2, 0xbb00000
	s_add_u32 s6, s96, s2
	s_addc_u32 s7, s97, 0
	s_add_u32 s2, s6, 0xc800
	s_addc_u32 s3, s7, 0
	v_cvt_pk_bf16_f32 v66, v18, v19
	v_cvt_pk_bf16_f32 v67, v20, v21
	global_store_dwordx2 v111, v[66:67], s[6:7] offset:0 nt
	v_cvt_pk_bf16_f32 v68, v22, v23
	v_cvt_pk_bf16_f32 v69, v24, v25
	global_store_dwordx2 v111, v[68:69], s[6:7] offset:16 nt
	v_cvt_pk_bf16_f32 v70, v26, v27
	v_cvt_pk_bf16_f32 v71, v28, v29
	global_store_dwordx2 v111, v[70:71], s[6:7] offset:32 nt
	v_cvt_pk_bf16_f32 v72, v30, v31
	v_cvt_pk_bf16_f32 v73, v32, v33
	global_store_dwordx2 v111, v[72:73], s[6:7] offset:48 nt
	v_cvt_pk_bf16_f32 v66, v50, v51
	v_cvt_pk_bf16_f32 v67, v52, v53
	global_store_dwordx2 v111, v[66:67], s[2:3] offset:0 nt
	v_cvt_pk_bf16_f32 v68, v54, v55
	v_cvt_pk_bf16_f32 v69, v56, v57
	global_store_dwordx2 v111, v[68:69], s[2:3] offset:16 nt
	v_cvt_pk_bf16_f32 v70, v58, v59
	v_cvt_pk_bf16_f32 v71, v60, v61
	global_store_dwordx2 v111, v[70:71], s[2:3] offset:32 nt
	v_cvt_pk_bf16_f32 v72, v62, v63
	v_cvt_pk_bf16_f32 v73, v64, v65
	global_store_dwordx2 v111, v[72:73], s[2:3] offset:48 nt
	s_branch .Lip_e1_end
.Lip_e1_vt:
	s_mul_hi_u32 s2, s0, 0x78787879
	s_lshr_b32 s2, s2, 4
	s_mul_i32 s3, s2, 34
	s_sub_u32 s3, s0, s3
	s_lshl_b32 s3, s3, 8
	s_mul_i32 s2, s2, 0x330000
	s_add_u32 s2, s2, s3
	s_sub_u32 s3, s16, 0xa20
	s_mul_i32 s3, s3, 0x2200
	s_add_u32 s2, s2, s3
	s_add_u32 s2, s2, 0xf020000
	s_add_u32 s6, s96, s2
	s_addc_u32 s7, s97, 0
	v_add_u32_e32 v74, 0x0, v112
	v_cvt_pk_bf16_f32 v66, v18, v18
	global_store_short v74, v66, s[6:7] nt
	v_add_u32_e32 v75, 0x2200, v112
	v_cvt_pk_bf16_f32 v68, v19, v19
	global_store_short v75, v68, s[6:7] nt
	v_add_u32_e32 v76, 0x4400, v112
	v_cvt_pk_bf16_f32 v70, v20, v20
	global_store_short v76, v70, s[6:7] nt
	v_add_u32_e32 v77, 0x6600, v112
	v_cvt_pk_bf16_f32 v72, v21, v21
	global_store_short v77, v72, s[6:7] nt
	v_add_u32_e32 v74, 0x11000, v112
	v_cvt_pk_bf16_f32 v66, v22, v22
	global_store_short v74, v66, s[6:7] nt
	v_add_u32_e32 v75, 0x13200, v112
	v_cvt_pk_bf16_f32 v68, v23, v23
	global_store_short v75, v68, s[6:7] nt
	v_add_u32_e32 v76, 0x15400, v112
	v_cvt_pk_bf16_f32 v70, v24, v24
	global_store_short v76, v70, s[6:7] nt
	v_add_u32_e32 v77, 0x17600, v112
	v_cvt_pk_bf16_f32 v72, v25, v25
	global_store_short v77, v72, s[6:7] nt
	v_add_u32_e32 v74, 0x22000, v112
	v_cvt_pk_bf16_f32 v66, v26, v26
	global_store_short v74, v66, s[6:7] nt
	v_add_u32_e32 v75, 0x24200, v112
	v_cvt_pk_bf16_f32 v68, v27, v27
	global_store_short v75, v68, s[6:7] nt
	v_add_u32_e32 v76, 0x26400, v112
	v_cvt_pk_bf16_f32 v70, v28, v28
	global_store_short v76, v70, s[6:7] nt
	v_add_u32_e32 v77, 0x28600, v112
	v_cvt_pk_bf16_f32 v72, v29, v29
	global_store_short v77, v72, s[6:7] nt
	v_add_u32_e32 v74, 0x33000, v112
	v_cvt_pk_bf16_f32 v66, v30, v30
	global_store_short v74, v66, s[6:7] nt
	v_add_u32_e32 v75, 0x35200, v112
	v_cvt_pk_bf16_f32 v68, v31, v31
	global_store_short v75, v68, s[6:7] nt
	v_add_u32_e32 v76, 0x37400, v112
	v_cvt_pk_bf16_f32 v70, v32, v32
	global_store_short v76, v70, s[6:7] nt
	v_add_u32_e32 v77, 0x39600, v112
	v_cvt_pk_bf16_f32 v72, v33, v33
	global_store_short v77, v72, s[6:7] nt
	v_add_u32_e32 v74, 0x40, v112
	v_cvt_pk_bf16_f32 v66, v50, v50
	global_store_short v74, v66, s[6:7] nt
	v_add_u32_e32 v75, 0x2240, v112
	v_cvt_pk_bf16_f32 v68, v51, v51
	global_store_short v75, v68, s[6:7] nt
	v_add_u32_e32 v76, 0x4440, v112
	v_cvt_pk_bf16_f32 v70, v52, v52
	global_store_short v76, v70, s[6:7] nt
	v_add_u32_e32 v77, 0x6640, v112
	v_cvt_pk_bf16_f32 v72, v53, v53
	global_store_short v77, v72, s[6:7] nt
	v_add_u32_e32 v74, 0x11040, v112
	v_cvt_pk_bf16_f32 v66, v54, v54
	global_store_short v74, v66, s[6:7] nt
	v_add_u32_e32 v75, 0x13240, v112
	v_cvt_pk_bf16_f32 v68, v55, v55
	global_store_short v75, v68, s[6:7] nt
	v_add_u32_e32 v76, 0x15440, v112
	v_cvt_pk_bf16_f32 v70, v56, v56
	global_store_short v76, v70, s[6:7] nt
	v_add_u32_e32 v77, 0x17640, v112
	v_cvt_pk_bf16_f32 v72, v57, v57
	global_store_short v77, v72, s[6:7] nt
	v_add_u32_e32 v74, 0x22040, v112
	v_cvt_pk_bf16_f32 v66, v58, v58
	global_store_short v74, v66, s[6:7] nt
	v_add_u32_e32 v75, 0x24240, v112
	v_cvt_pk_bf16_f32 v68, v59, v59
	global_store_short v75, v68, s[6:7] nt
	v_add_u32_e32 v76, 0x26440, v112
	v_cvt_pk_bf16_f32 v70, v60, v60
	global_store_short v76, v70, s[6:7] nt
	v_add_u32_e32 v77, 0x28640, v112
	v_cvt_pk_bf16_f32 v72, v61, v61
	global_store_short v77, v72, s[6:7] nt
	v_add_u32_e32 v74, 0x33040, v112
	v_cvt_pk_bf16_f32 v66, v62, v62
	global_store_short v74, v66, s[6:7] nt
	v_add_u32_e32 v75, 0x35240, v112
	v_cvt_pk_bf16_f32 v68, v63, v63
	global_store_short v75, v68, s[6:7] nt
	v_add_u32_e32 v76, 0x37440, v112
	v_cvt_pk_bf16_f32 v70, v64, v64
	global_store_short v76, v70, s[6:7] nt
	v_add_u32_e32 v77, 0x39640, v112
	v_cvt_pk_bf16_f32 v72, v65, v65
	global_store_short v77, v72, s[6:7] nt
